# w_out / ffn_out main epilogues: gamma/beta piece and residual-row loads issued before the K-loop's closing barrier
# speedup vs baseline: 1.0048x; 1.0048x over previous
; #define PG8_STAGE(bufoff, gbase, voff) do { _Pragma("unroll") for (int _i = 0; _i < 2; ++_i) \
;         __builtin_amdgcn_global_load_lds((const unsigned*)((const char*)(gbase) + (voff)[_i]), (PG8_LAS unsigned*)(lds + (bufoff) + ldsw + _i * 8192), 16, 0, 0); } while (0)
; #define PG8_LDA(dst, b, h) do { _Pragma("unroll") for (int m = 0; m < 4; ++m) _Pragma("unroll") for (int k = 0; k < 2; ++k) dst[m][k] = *(const PG8_LAS bf16x8*)(lds + PG8_SA(b, h) + aoff + m * 2048 + k * 1024); } while (0)
; #define PG8_LDB(dst, b, h) do { _Pragma("unroll") for (int n = 0; n < 2; ++n) _Pragma("unroll") for (int k = 0; k < 2; ++k) dst[n][k] = *(const PG8_LAS bf16x8*)(lds + PG8_SB(b, h) + boff + n * 2048 + k * 1024); } while (0)
; #define PG8_MMA(ai, bj, At, Bt) do { __builtin_amdgcn_s_setprio(1); _Pragma("unroll") for (int m = 0; m < 4; ++m) _Pragma("unroll") for (int n = 0; n < 2; ++n) _Pragma("unroll") for (int k = 0; k < 2; ++k) \
;         acc[ai][bj][m][n] = __builtin_amdgcn_mfma_f32_16x16x32_bf16(Bt[n][k], At[m][k], acc[ai][bj][m][n], 0, 0, 0); __builtin_amdgcn_s_setprio(0); } while (0)
; #define PG8_WAIT_V(n) asm volatile("s_waitcnt vmcnt(" #n ")" ::: "memory")
; #define PG8_WAIT_L(n) asm volatile("s_waitcnt lgkmcnt(" #n ")" ::: "memory")
; #define PG8_BAR __builtin_amdgcn_s_barrier()
; #define PG8_SCHED __builtin_amdgcn_sched_barrier(0)
; template <class Epi, class Sched, bool ALIGN_EPI = false, bool SP2 = false>
; __device__ __forceinline__ void gemm_phase(PG8_LAS unsigned char* lds, const Gemm g, const Sched& S, const Epi& E, int tid_in) {
;     ...
;             PG8_LDB(B0, 0, 0); PG8_LDB(B1, 0, 1); PG8_SCHED; PG8_LDA(At, 0, 0); PG8_STAGE(PG8_SA(1, 1), a1 + hstep, voffA);
;             PG8_WAIT_V(8); PG8_WAIT_L(0); PG8_BAR; PG8_MMA(0, 0, At, B0); PG8_MMA(0, 1, At, B1); PG8_BAR; PG8_SCHED;
;             PG8_LDA(At, 0, 1); PG8_STAGE(PG8_SB(0, 0), b2, voffB); PG8_STAGE(PG8_SB(0, 1), b2 + hstep, voffB); PG8_STAGE(PG8_SA(0, 0), a2, voffA);
;             PG8_WAIT_V(8); PG8_WAIT_L(0); PG8_BAR; PG8_MMA(1, 0, At, B0); PG8_MMA(1, 1, At, B1); PG8_BAR; PG8_SCHED;
.LBB0_1432:
	s_add_u32 s42, s40, 0xfffc0080
	s_addc_u32 s43, s41, -1
	s_add_i32 s79, 0, 0x10000
	s_cmp_eq_u32 s78, 12
	s_cselect_b32 s67, s0, s43
	s_cselect_b32 s66, s1, s42
	s_cselect_b32 s43, s5, s77
	s_cselect_b32 s42, s59, s61
	s_add_i32 s82, 0, 0x14000
	v_add_u32_e32 v142, s79, v210
	v_add_u32_e32 v158, s82, v210
	ds_read_b128 v[114:117], v142
	ds_read_b128 v[118:121], v142 offset:1024
	ds_read_b128 v[138:141], v142 offset:2048
	ds_read_b128 v[142:145], v142 offset:3072
	ds_read_b128 v[146:149], v158
	ds_read_b128 v[150:153], v158 offset:1024
	ds_read_b128 v[154:157], v158 offset:2048
	ds_read_b128 v[158:161], v158 offset:3072
	v_lshl_add_u64 v[184:185], s[40:41], 0, v[168:169]
	s_add_i32 m0, s9, 0xc000
	ds_read_b128 v[172:175], v211
	ds_read_b128 v[176:179], v211 offset:1024
	ds_read_b128 v[180:183], v211 offset:2048
	ds_read_b128 v[190:193], v211 offset:3072
	ds_read_b128 v[194:197], v211 offset:4096
	ds_read_b128 v[198:201], v211 offset:5120
	ds_read_b128 v[202:205], v211 offset:6144
	ds_read_b128 v[212:215], v211 offset:7168
	global_load_lds_dwordx4 v[184:185], off
	v_lshl_add_u64 v[184:185], s[40:41], 0, v[170:171]
	s_add_i32 m0, s9, 0xe000
	s_nop 0
	global_load_lds_dwordx4 v[184:185], off
	s_waitcnt vmcnt(8)
	s_waitcnt lgkmcnt(0)
	s_barrier
	s_setprio 1
	s_waitcnt lgkmcnt(0)
	v_mfma_f32_16x16x32_bf16 v[134:137], v[114:117], v[172:175], v[134:137]
	v_mfma_f32_16x16x32_bf16 v[130:133], v[138:141], v[172:175], v[130:133]
	v_mfma_f32_16x16x32_bf16 v[110:113], v[114:117], v[180:183], v[110:113]
	v_mfma_f32_16x16x32_bf16 v[106:109], v[138:141], v[180:183], v[106:109]
	v_mfma_f32_16x16x32_bf16 v[94:97], v[114:117], v[194:197], v[94:97]
	v_mfma_f32_16x16x32_bf16 v[90:93], v[138:141], v[194:197], v[90:93]
	v_mfma_f32_16x16x32_bf16 v[76:79], v[114:117], v[202:205], v[76:79]
	v_mfma_f32_16x16x32_bf16 v[72:75], v[138:141], v[202:205], v[72:75]
	v_mfma_f32_16x16x32_bf16 v[134:137], v[118:121], v[176:179], v[134:137]
	v_mfma_f32_16x16x32_bf16 v[130:133], v[142:145], v[176:179], v[130:133]
	v_mfma_f32_16x16x32_bf16 v[110:113], v[118:121], v[190:193], v[110:113]
	v_mfma_f32_16x16x32_bf16 v[106:109], v[142:145], v[190:193], v[106:109]
	v_mfma_f32_16x16x32_bf16 v[94:97], v[118:121], v[198:201], v[94:97]
	v_mfma_f32_16x16x32_bf16 v[90:93], v[142:145], v[198:201], v[90:93]
	v_mfma_f32_16x16x32_bf16 v[76:79], v[118:121], v[212:215], v[76:79]
	v_mfma_f32_16x16x32_bf16 v[72:75], v[142:145], v[212:215], v[72:75]
	v_mfma_f32_16x16x32_bf16 v[126:129], v[146:149], v[172:175], v[126:129]
	v_mfma_f32_16x16x32_bf16 v[122:125], v[154:157], v[172:175], v[122:125]
	v_mfma_f32_16x16x32_bf16 v[102:105], v[146:149], v[180:183], v[102:105]
	v_mfma_f32_16x16x32_bf16 v[98:101], v[154:157], v[180:183], v[98:101]
	v_mfma_f32_16x16x32_bf16 v[86:89], v[146:149], v[194:197], v[86:89]
	v_mfma_f32_16x16x32_bf16 v[82:85], v[154:157], v[194:197], v[82:85]
	v_mfma_f32_16x16x32_bf16 v[68:71], v[146:149], v[202:205], v[68:71]
	v_mfma_f32_16x16x32_bf16 v[64:67], v[154:157], v[202:205], v[64:67]
	v_mfma_f32_16x16x32_bf16 v[126:129], v[150:153], v[176:179], v[126:129]
	v_mfma_f32_16x16x32_bf16 v[122:125], v[158:161], v[176:179], v[122:125]
	v_mfma_f32_16x16x32_bf16 v[102:105], v[150:153], v[190:193], v[102:105]
	v_mfma_f32_16x16x32_bf16 v[98:101], v[158:161], v[190:193], v[98:101]
	v_mfma_f32_16x16x32_bf16 v[86:89], v[150:153], v[198:201], v[86:89]
	v_mfma_f32_16x16x32_bf16 v[82:85], v[158:161], v[198:201], v[82:85]
	v_mfma_f32_16x16x32_bf16 v[68:71], v[150:153], v[212:215], v[68:71]
	v_mfma_f32_16x16x32_bf16 v[64:67], v[158:161], v[212:215], v[64:67]
	s_setprio 0
	s_barrier
	s_add_i32 s79, s79, s14
	v_lshl_add_u64 v[184:185], s[42:43], 0, v[80:81]
	s_mov_b32 m0, s79
	ds_read_b128 v[172:175], v211 offset:16384
	ds_read_b128 v[176:179], v211 offset:17408
	ds_read_b128 v[180:183], v211 offset:18432
	ds_read_b128 v[190:193], v211 offset:19456
	ds_read_b128 v[194:197], v211 offset:20480
	ds_read_b128 v[198:201], v211 offset:21504
	ds_read_b128 v[202:205], v211 offset:22528
	ds_read_b128 v[212:215], v211 offset:23552
	global_load_lds_dwordx4 v[184:185], off
	s_add_i32 m0, s79, 0x2000
	s_add_u32 s80, s42, 0x40000
	v_lshl_add_u64 v[186:187], s[42:43], 0, v[166:167]
	s_addc_u32 s81, s43, 0
	s_add_i32 s79, s82, s14
	global_load_lds_dwordx4 v[186:187], off
	v_lshl_add_u64 v[188:189], s[80:81], 0, v[80:81]
	s_mov_b32 m0, s79
	v_lshl_add_u64 v[206:207], s[66:67], 0, v[164:165]
	global_load_lds_dwordx4 v[188:189], off
	v_lshl_add_u64 v[188:189], s[80:81], 0, v[166:167]
	s_add_i32 m0, s79, 0x2000
	s_nop 0
	global_load_lds_dwordx4 v[188:189], off
	v_lshl_add_u64 v[188:189], s[66:67], 0, v[162:163]
	s_mov_b32 m0, s9
	s_nop 0
	global_load_lds_dwordx4 v[188:189], off
	s_mov_b32 m0, s15
	s_nop 0
	global_load_lds_dwordx4 v[206:207], off
	s_waitcnt vmcnt(8)
	s_waitcnt lgkmcnt(0)
	s_barrier
; #define PG8_STAGE(bufoff, gbase, voff) do { _Pragma("unroll") for (int _i = 0; _i < 2; ++_i) \
;         __builtin_amdgcn_global_load_lds((const unsigned*)((const char*)(gbase) + (voff)[_i]), (PG8_LAS unsigned*)(lds + (bufoff) + ldsw + _i * 8192), 16, 0, 0); } while (0)
; #define PG8_LDA(dst, b, h) do { _Pragma("unroll") for (int m = 0; m < 4; ++m) _Pragma("unroll") for (int k = 0; k < 2; ++k) dst[m][k] = *(const PG8_LAS bf16x8*)(lds + PG8_SA(b, h) + aoff + m * 2048 + k * 1024); } while (0)
; #define PG8_LDB(dst, b, h) do { _Pragma("unroll") for (int n = 0; n < 2; ++n) _Pragma("unroll") for (int k = 0; k < 2; ++k) dst[n][k] = *(const PG8_LAS bf16x8*)(lds + PG8_SB(b, h) + boff + n * 2048 + k * 1024); } while (0)
; #define PG8_MMA(ai, bj, At, Bt) do { __builtin_amdgcn_s_setprio(1); _Pragma("unroll") for (int m = 0; m < 4; ++m) _Pragma("unroll") for (int n = 0; n < 2; ++n) _Pragma("unroll") for (int k = 0; k < 2; ++k) \
;         acc[ai][bj][m][n] = __builtin_amdgcn_mfma_f32_16x16x32_bf16(Bt[n][k], At[m][k], acc[ai][bj][m][n], 0, 0, 0); __builtin_amdgcn_s_setprio(0); } while (0)
; #define PG8_WAIT_V(n) asm volatile("s_waitcnt vmcnt(" #n ")" ::: "memory")
; #define PG8_WAIT_L(n) asm volatile("s_waitcnt lgkmcnt(" #n ")" ::: "memory")
; #define PG8_BAR __builtin_amdgcn_s_barrier()
; #define PG8_SCHED __builtin_amdgcn_sched_barrier(0)
; template <class Epi, class Sched, bool ALIGN_EPI = false, bool SP2 = false>
; __device__ __forceinline__ void gemm_phase(PG8_LAS unsigned char* lds, const Gemm g, const Sched& S, const Epi& E, int tid_in) {
;     ...
;             PG8_WAIT_V(8); PG8_WAIT_L(0); PG8_BAR; PG8_MMA(1, 0, At, B0); PG8_MMA(1, 1, At, B1); PG8_BAR; PG8_SCHED;
;             PG8_LDB(B0, 1, 0); PG8_LDB(B1, 1, 1); PG8_SCHED; PG8_LDA(At, 1, 0); PG8_STAGE(PG8_SA(0, 1), a2 + hstep, voffA);
;             PG8_WAIT_V(8); PG8_WAIT_L(0); PG8_BAR; PG8_MMA(0, 0, At, B0); PG8_MMA(0, 1, At, B1); PG8_BAR; PG8_SCHED;
	s_setprio 1
	s_waitcnt lgkmcnt(0)
	v_mfma_f32_16x16x32_bf16 v[60:63], v[114:117], v[172:175], v[60:63]
	v_mfma_f32_16x16x32_bf16 v[56:59], v[138:141], v[172:175], v[56:59]
	v_mfma_f32_16x16x32_bf16 v[44:47], v[114:117], v[180:183], v[44:47]
	v_mfma_f32_16x16x32_bf16 v[40:43], v[138:141], v[180:183], v[40:43]
	v_mfma_f32_16x16x32_bf16 v[28:31], v[114:117], v[194:197], v[28:31]
	v_mfma_f32_16x16x32_bf16 v[24:27], v[138:141], v[194:197], v[24:27]
	v_mfma_f32_16x16x32_bf16 v[12:15], v[114:117], v[202:205], v[12:15]
	v_mfma_f32_16x16x32_bf16 v[8:11], v[138:141], v[202:205], v[8:11]
	v_mfma_f32_16x16x32_bf16 v[60:63], v[118:121], v[176:179], v[60:63]
	v_mfma_f32_16x16x32_bf16 v[56:59], v[142:145], v[176:179], v[56:59]
	v_mfma_f32_16x16x32_bf16 v[44:47], v[118:121], v[190:193], v[44:47]
	v_mfma_f32_16x16x32_bf16 v[40:43], v[142:145], v[190:193], v[40:43]
	v_mfma_f32_16x16x32_bf16 v[28:31], v[118:121], v[198:201], v[28:31]
	v_mfma_f32_16x16x32_bf16 v[24:27], v[142:145], v[198:201], v[24:27]
	v_mfma_f32_16x16x32_bf16 v[12:15], v[118:121], v[212:215], v[12:15]
	v_mfma_f32_16x16x32_bf16 v[8:11], v[142:145], v[212:215], v[8:11]
	v_mfma_f32_16x16x32_bf16 v[52:55], v[146:149], v[172:175], v[52:55]
	v_mfma_f32_16x16x32_bf16 v[48:51], v[154:157], v[172:175], v[48:51]
	v_mfma_f32_16x16x32_bf16 v[36:39], v[146:149], v[180:183], v[36:39]
	v_mfma_f32_16x16x32_bf16 v[32:35], v[154:157], v[180:183], v[32:35]
	v_mfma_f32_16x16x32_bf16 v[20:23], v[146:149], v[194:197], v[20:23]
	v_mfma_f32_16x16x32_bf16 v[16:19], v[154:157], v[194:197], v[16:19]
	v_mfma_f32_16x16x32_bf16 v[4:7], v[146:149], v[202:205], v[4:7]
	v_mfma_f32_16x16x32_bf16 v[0:3], v[154:157], v[202:205], v[0:3]
	v_mfma_f32_16x16x32_bf16 v[52:55], v[150:153], v[176:179], v[52:55]
	v_mfma_f32_16x16x32_bf16 v[48:51], v[158:161], v[176:179], v[48:51]
	v_mfma_f32_16x16x32_bf16 v[36:39], v[150:153], v[190:193], v[36:39]
	v_mfma_f32_16x16x32_bf16 v[32:35], v[158:161], v[190:193], v[32:35]
	v_mfma_f32_16x16x32_bf16 v[20:23], v[150:153], v[198:201], v[20:23]
	v_mfma_f32_16x16x32_bf16 v[16:19], v[158:161], v[198:201], v[16:19]
	v_mfma_f32_16x16x32_bf16 v[4:7], v[150:153], v[212:215], v[4:7]
	v_mfma_f32_16x16x32_bf16 v[0:3], v[158:161], v[212:215], v[0:3]
	s_setprio 0
	s_barrier
	s_add_i32 s79, 0, 0x18000
	s_add_i32 s80, 0, 0x1c000
	v_add_u32_e32 v142, s79, v210
	v_add_u32_e32 v158, s80, v210
	ds_read_b128 v[114:117], v142
	ds_read_b128 v[118:121], v142 offset:1024
	ds_read_b128 v[138:141], v142 offset:2048
	ds_read_b128 v[142:145], v142 offset:3072
	ds_read_b128 v[146:149], v158
	ds_read_b128 v[150:153], v158 offset:1024
	ds_read_b128 v[154:157], v158 offset:2048
	ds_read_b128 v[158:161], v158 offset:3072
	s_add_u32 s66, s66, 0x40000
	s_addc_u32 s67, s67, 0
	s_mov_b32 m0, s16
	v_lshl_add_u64 v[226:227], s[66:67], 0, v[162:163]
	ds_read_b128 v[172:175], v211 offset:32768
	ds_read_b128 v[176:179], v211 offset:33792
	ds_read_b128 v[180:183], v211 offset:34816
	ds_read_b128 v[190:193], v211 offset:35840
	ds_read_b128 v[194:197], v211 offset:36864
	ds_read_b128 v[198:201], v211 offset:37888
	ds_read_b128 v[202:205], v211 offset:38912
	ds_read_b128 v[212:215], v211 offset:39936
	global_load_lds_dwordx4 v[226:227], off
	v_lshl_add_u64 v[226:227], s[66:67], 0, v[164:165]
	s_mov_b32 m0, s17
	s_nop 0
	global_load_lds_dwordx4 v[226:227], off
	s_waitcnt vmcnt(8)
	s_waitcnt lgkmcnt(0)
	s_barrier
	s_setprio 1
	s_waitcnt lgkmcnt(0)
	v_mfma_f32_16x16x32_bf16 v[134:137], v[114:117], v[172:175], v[134:137]
	v_mfma_f32_16x16x32_bf16 v[130:133], v[138:141], v[172:175], v[130:133]
	v_mfma_f32_16x16x32_bf16 v[110:113], v[114:117], v[180:183], v[110:113]
	v_mfma_f32_16x16x32_bf16 v[106:109], v[138:141], v[180:183], v[106:109]
	v_mfma_f32_16x16x32_bf16 v[94:97], v[114:117], v[194:197], v[94:97]
	v_mfma_f32_16x16x32_bf16 v[90:93], v[138:141], v[194:197], v[90:93]
	v_mfma_f32_16x16x32_bf16 v[76:79], v[114:117], v[202:205], v[76:79]
	v_mfma_f32_16x16x32_bf16 v[72:75], v[138:141], v[202:205], v[72:75]
	v_mfma_f32_16x16x32_bf16 v[134:137], v[118:121], v[176:179], v[134:137]
	v_mfma_f32_16x16x32_bf16 v[130:133], v[142:145], v[176:179], v[130:133]
	v_mfma_f32_16x16x32_bf16 v[110:113], v[118:121], v[190:193], v[110:113]
	v_mfma_f32_16x16x32_bf16 v[106:109], v[142:145], v[190:193], v[106:109]
	v_mfma_f32_16x16x32_bf16 v[94:97], v[118:121], v[198:201], v[94:97]
	v_mfma_f32_16x16x32_bf16 v[90:93], v[142:145], v[198:201], v[90:93]
	v_mfma_f32_16x16x32_bf16 v[76:79], v[118:121], v[212:215], v[76:79]
	v_mfma_f32_16x16x32_bf16 v[72:75], v[142:145], v[212:215], v[72:75]
	v_mfma_f32_16x16x32_bf16 v[126:129], v[146:149], v[172:175], v[126:129]
	v_mfma_f32_16x16x32_bf16 v[122:125], v[154:157], v[172:175], v[122:125]
	v_mfma_f32_16x16x32_bf16 v[102:105], v[146:149], v[180:183], v[102:105]
	v_mfma_f32_16x16x32_bf16 v[98:101], v[154:157], v[180:183], v[98:101]
	v_mfma_f32_16x16x32_bf16 v[86:89], v[146:149], v[194:197], v[86:89]
	v_mfma_f32_16x16x32_bf16 v[82:85], v[154:157], v[194:197], v[82:85]
	v_mfma_f32_16x16x32_bf16 v[68:71], v[146:149], v[202:205], v[68:71]
	v_mfma_f32_16x16x32_bf16 v[64:67], v[154:157], v[202:205], v[64:67]
	v_mfma_f32_16x16x32_bf16 v[126:129], v[150:153], v[176:179], v[126:129]
	v_mfma_f32_16x16x32_bf16 v[122:125], v[158:161], v[176:179], v[122:125]
	v_mfma_f32_16x16x32_bf16 v[102:105], v[150:153], v[190:193], v[102:105]
	v_mfma_f32_16x16x32_bf16 v[98:101], v[158:161], v[190:193], v[98:101]
	v_mfma_f32_16x16x32_bf16 v[86:89], v[150:153], v[198:201], v[86:89]
	v_mfma_f32_16x16x32_bf16 v[82:85], v[158:161], v[198:201], v[82:85]
	v_mfma_f32_16x16x32_bf16 v[68:71], v[150:153], v[212:215], v[68:71]
	v_mfma_f32_16x16x32_bf16 v[64:67], v[158:161], v[212:215], v[64:67]
	s_setprio 0
	s_barrier
; #define PG8_STAGE(bufoff, gbase, voff) do { _Pragma("unroll") for (int _i = 0; _i < 2; ++_i) \
;         __builtin_amdgcn_global_load_lds((const unsigned*)((const char*)(gbase) + (voff)[_i]), (PG8_LAS unsigned*)(lds + (bufoff) + ldsw + _i * 8192), 16, 0, 0); } while (0)
; #define PG8_LDA(dst, b, h) do { _Pragma("unroll") for (int m = 0; m < 4; ++m) _Pragma("unroll") for (int k = 0; k < 2; ++k) dst[m][k] = *(const PG8_LAS bf16x8*)(lds + PG8_SA(b, h) + aoff + m * 2048 + k * 1024); } while (0)
; #define PG8_MMA(ai, bj, At, Bt) do { __builtin_amdgcn_s_setprio(1); _Pragma("unroll") for (int m = 0; m < 4; ++m) _Pragma("unroll") for (int n = 0; n < 2; ++n) _Pragma("unroll") for (int k = 0; k < 2; ++k) \
;         acc[ai][bj][m][n] = __builtin_amdgcn_mfma_f32_16x16x32_bf16(Bt[n][k], At[m][k], acc[ai][bj][m][n], 0, 0, 0); __builtin_amdgcn_s_setprio(0); } while (0)
; #define PG8_WAIT_V(n) asm volatile("s_waitcnt vmcnt(" #n ")" ::: "memory")
; #define PG8_WAIT_L(n) asm volatile("s_waitcnt lgkmcnt(" #n ")" ::: "memory")
; #define PG8_BAR __builtin_amdgcn_s_barrier()
; #define PG8_SCHED __builtin_amdgcn_sched_barrier(0)
; template <class Epi, class Sched, bool ALIGN_EPI = false, bool SP2 = false>
; __device__ __forceinline__ void gemm_phase(PG8_LAS unsigned char* lds, const Gemm g, const Sched& S, const Epi& E, int tid_in) {
;     ...
;             PG8_LDA(At, 1, 1); PG8_STAGE(PG8_SB(1, 0), b3, voffB); PG8_STAGE(PG8_SB(1, 1), b3 + hstep, voffB); PG8_STAGE(PG8_SA(1, 0), a3, voffA);
;             PG8_WAIT_V(8); PG8_WAIT_L(0); PG8_BAR; PG8_MMA(1, 0, At, B0); PG8_MMA(1, 1, At, B1); PG8_BAR; PG8_SCHED;
;     __device__ __forceinline__ void operator()(const pg8::f32x4 (&acc)[2][2][4][2], const pg8::Unit& u, int wr, int wc, int fr, int fq) const {
;     ...
;         const int col0 = u.pn * 256 + wc * 32 + 8 * fq;
; #pragma unroll
;         for (int ai = 0; ai < 2; ++ai) {
;             u32x4 zx[4][2];
; #pragma unroll
;             for (int m = 0; m < 4; ++m)
; #pragma unroll
;                 for (int bj = 0; bj < 2; ++bj) zx[m][bj] = *(const u32x4*)(ZB + (size_t)(u.pm * 256 + ai * 128 + wr * 64 + m * 16 + fr) * 1024 + col0 + bj * 128);
	s_add_i32 s66, s79, s14
	v_lshl_add_u64 v[184:185], v[184:185], 0, s[6:7]
	s_mov_b32 m0, s66
	ds_read_b128 v[172:175], v211 offset:49152
	ds_read_b128 v[176:179], v211 offset:50176
	ds_read_b128 v[180:183], v211 offset:51200
	ds_read_b128 v[190:193], v211 offset:52224
	ds_read_b128 v[194:197], v211 offset:53248
	ds_read_b128 v[198:201], v211 offset:54272
	ds_read_b128 v[202:205], v211 offset:55296
	ds_read_b128 v[212:215], v211 offset:56320
	global_load_lds_dwordx4 v[184:185], off
	s_add_i32 m0, s66, 0x2000
	s_add_u32 s42, s42, 0x40080
	v_lshl_add_u64 v[184:185], v[186:187], 0, s[6:7]
	s_addc_u32 s43, s43, 0
	s_add_i32 s66, s80, s14
	global_load_lds_dwordx4 v[184:185], off
	v_lshl_add_u64 v[184:185], s[42:43], 0, v[80:81]
	s_mov_b32 m0, s66
	s_nop 0
	global_load_lds_dwordx4 v[184:185], off
	v_lshl_add_u64 v[184:185], s[42:43], 0, v[166:167]
	s_add_i32 m0, s66, 0x2000
	s_nop 0
	global_load_lds_dwordx4 v[184:185], off
	v_lshl_add_u64 v[184:185], v[188:189], 0, s[6:7]
	s_mov_b32 m0, s69
	s_nop 0
	global_load_lds_dwordx4 v[184:185], off
	v_lshl_add_u64 v[184:185], v[206:207], 0, s[6:7]
	s_mov_b32 m0, s70
	s_nop 0
	global_load_lds_dwordx4 v[184:185], off
	s_waitcnt vmcnt(8)
	s_waitcnt lgkmcnt(0)
	s_barrier
	s_setprio 1
	s_waitcnt lgkmcnt(0)
	v_mfma_f32_16x16x32_bf16 v[60:63], v[114:117], v[172:175], v[60:63]
	v_mfma_f32_16x16x32_bf16 v[56:59], v[138:141], v[172:175], v[56:59]
	v_mfma_f32_16x16x32_bf16 v[44:47], v[114:117], v[180:183], v[44:47]
	v_mfma_f32_16x16x32_bf16 v[40:43], v[138:141], v[180:183], v[40:43]
	v_mfma_f32_16x16x32_bf16 v[28:31], v[114:117], v[194:197], v[28:31]
	v_mfma_f32_16x16x32_bf16 v[24:27], v[138:141], v[194:197], v[24:27]
	v_mfma_f32_16x16x32_bf16 v[12:15], v[114:117], v[202:205], v[12:15]
	v_mfma_f32_16x16x32_bf16 v[8:11], v[138:141], v[202:205], v[8:11]
	v_mfma_f32_16x16x32_bf16 v[60:63], v[118:121], v[176:179], v[60:63]
	v_mfma_f32_16x16x32_bf16 v[56:59], v[142:145], v[176:179], v[56:59]
	v_mfma_f32_16x16x32_bf16 v[44:47], v[118:121], v[190:193], v[44:47]
	v_mfma_f32_16x16x32_bf16 v[40:43], v[142:145], v[190:193], v[40:43]
	v_mfma_f32_16x16x32_bf16 v[28:31], v[118:121], v[198:201], v[28:31]
	v_mfma_f32_16x16x32_bf16 v[24:27], v[142:145], v[198:201], v[24:27]
	v_mfma_f32_16x16x32_bf16 v[12:15], v[118:121], v[212:215], v[12:15]
	v_mfma_f32_16x16x32_bf16 v[8:11], v[142:145], v[212:215], v[8:11]
	v_mfma_f32_16x16x32_bf16 v[52:55], v[146:149], v[172:175], v[52:55]
	v_mfma_f32_16x16x32_bf16 v[48:51], v[154:157], v[172:175], v[48:51]
	v_mfma_f32_16x16x32_bf16 v[36:39], v[146:149], v[180:183], v[36:39]
	v_mfma_f32_16x16x32_bf16 v[32:35], v[154:157], v[180:183], v[32:35]
	v_mfma_f32_16x16x32_bf16 v[20:23], v[146:149], v[194:197], v[20:23]
	v_mfma_f32_16x16x32_bf16 v[16:19], v[154:157], v[194:197], v[16:19]
	v_mfma_f32_16x16x32_bf16 v[4:7], v[146:149], v[202:205], v[4:7]
	v_mfma_f32_16x16x32_bf16 v[0:3], v[154:157], v[202:205], v[0:3]
	v_mfma_f32_16x16x32_bf16 v[52:55], v[150:153], v[176:179], v[52:55]
	v_mfma_f32_16x16x32_bf16 v[48:51], v[158:161], v[176:179], v[48:51]
	v_mfma_f32_16x16x32_bf16 v[36:39], v[150:153], v[190:193], v[36:39]
	v_mfma_f32_16x16x32_bf16 v[32:35], v[158:161], v[190:193], v[32:35]
	v_mfma_f32_16x16x32_bf16 v[20:23], v[150:153], v[198:201], v[20:23]
	v_mfma_f32_16x16x32_bf16 v[16:19], v[158:161], v[198:201], v[16:19]
	v_mfma_f32_16x16x32_bf16 v[4:7], v[150:153], v[212:215], v[4:7]
	v_mfma_f32_16x16x32_bf16 v[0:3], v[158:161], v[212:215], v[0:3]
	s_setprio 0
	s_barrier
	s_add_i32 s78, s78, 2
	s_add_u32 s40, s40, 0x100
	s_addc_u32 s41, s41, 0
	s_add_u32 s61, s61, 0x100
	s_addc_u32 s77, s77, 0
	s_cmp_gt_u32 s78, 13
	s_cbranch_scc0 .LBB0_1432
	v_mov_b32_e32 v196, v209
	v_mov_b32_e32 v213, v208
	s_lshl_b32 s0, s4, 8
	s_or_b32 s0, s0, s19
	s_lshl_b32 s42, s8, 8
	v_add_u32_e32 v212, s18, v196
	v_lshl_add_u32 v172, v213, 3, s0
	v_and_b32_e32 v186, 0xffffff00, v172
	v_and_b32_e32 v187, 0xff, v216
	v_add_lshl_u32 v186, v186, v187, 2
	v_mov_b32_e32 v187, 0
	v_cmp_gt_u32_e32 vcc, 0x100, v216
	v_mov_b32_e32 v188, s50
	v_mov_b32_e32 v189, s51
	s_and_saveexec_b64 vcc, vcc
	v_mov_b32_e32 v188, s48
	v_mov_b32_e32 v189, s49
	s_mov_b64 exec, vcc
	v_lshl_add_u64 v[188:189], v[188:189], 0, v[186:187]
	global_load_dword v186, v[188:189], off
	v_lshlrev_b32_e32 v187, 2, v216
	v_add_u32_e32 v187, 0x21000, v187
	v_and_b32_e32 v80, 0xff, v172
	v_lshlrev_b32_e32 v80, 2, v80
	v_add_u32_e32 v80, 0x21000, v80
	v_add_u32_e32 v176, s42, v212
	v_ashrrev_i32_e32 v173, 31, v172
	v_ashrrev_i32_e32 v177, 31, v176
	v_add_u32_e32 v190, 16, v176
	v_lshl_add_u64 v[174:175], v[172:173], 1, s[20:21]
	v_lshlrev_b64 v[194:195], 11, v[176:177]
	v_ashrrev_i32_e32 v191, 31, v190
	v_add_u32_e32 v182, 32, v176
	v_lshl_add_u64 v[114:115], v[174:175], 0, v[194:195]
	v_lshlrev_b64 v[192:193], 11, v[190:191]
	v_ashrrev_i32_e32 v183, 31, v182
	v_add_u32_e32 v178, 48, v176
	global_load_dwordx4 v[158:161], v[114:115], off
	global_load_dwordx4 v[154:157], v[114:115], off offset:256
	v_lshl_add_u64 v[114:115], v[174:175], 0, v[192:193]
	v_lshlrev_b64 v[184:185], 11, v[182:183]
	v_ashrrev_i32_e32 v179, 31, v178
	global_load_dwordx4 v[150:153], v[114:115], off
	global_load_dwordx4 v[146:149], v[114:115], off offset:256
	v_lshl_add_u64 v[114:115], v[174:175], 0, v[184:185]
	v_lshlrev_b64 v[180:181], 11, v[178:179]
	global_load_dwordx4 v[142:145], v[114:115], off
	global_load_dwordx4 v[138:141], v[114:115], off offset:256
	v_lshl_add_u64 v[114:115], v[174:175], 0, v[180:181]
	global_load_dwordx4 v[118:121], v[114:115], off
	s_nop 0
	global_load_dwordx4 v[114:117], v[114:115], off offset:256
	s_and_b64 vcc, exec, s[54:55]
	s_cbranch_vccz .LBB0_1435
	s_barrier
; __device__ __forceinline__ void ln_table(const float* st, int pm, int key, int wr, int wc, int fr, int fq) {
;     ...
;     if (st) {
;         const int want = key * 128 + pm + 1;
;         if (__builtin_amdgcn_readfirstlane(*kw) != want) {
;             if (t < 256) {
;                 const f32x4* p = (const f32x4*)(st + ((size_t)(pm * 256 + t)) * 32);
;                 float s = 0.f, q = 0.f;
; #pragma unroll
;                 for (int i = 0; i < 8; ++i) { const f32x4 v = p[i]; s += v[0] + v[2]; q += v[1] + v[3]; }
;                 const float mu = s * (1.f / D);
;                 tab[t] = (f32x2v){mu, __builtin_amdgcn_rsqf(fmaxf(q * (1.f / D) - mu * mu, 0.f) + LN_EPS)};
;             }
;             asm volatile("s_waitcnt lgkmcnt(0)" ::: "memory"); __builtin_amdgcn_s_barrier(); asm volatile("" ::: "memory");
;             if (t == 0) *kw = want;
.LBB0_1435:
	s_waitcnt vmcnt(8)
	ds_write_b32 v187, v186
	v_cndmask_b32_e64 v186, 0, 1, s[56:57]
	v_cmp_ne_u32_e64 s[40:41], 1, v186
	s_andn2_b64 vcc, exec, s[56:57]
	s_cbranch_vccnz .LBB0_1443
	ds_read_b32 v186, v223
	s_add_i32 s5, s75, s8
	s_waitcnt lgkmcnt(0)
	v_readfirstlane_b32 s0, v186
	s_cmp_eq_u32 s0, s5
	s_cbranch_scc1 .LBB0_1442
	v_lshlrev_b32_e32 v186, 4, v213
	v_add3_u32 v196, s71, v196, v186
	s_movk_i32 s0, 0x100
	v_cmp_gt_i32_e32 vcc, s0, v196
	s_and_saveexec_b64 s[0:1], vcc
	s_cbranch_execz .LBB0_1439
	v_add_u32_e32 v186, s42, v196
	v_ashrrev_i32_e32 v187, 31, v186
	v_lshlrev_b64 v[186:187], 7, v[186:187]
	v_lshl_add_u64 v[186:187], s[46:47], 0, v[186:187]
	global_load_dwordx4 v[198:201], v[186:187], off
	global_load_dwordx4 v[202:205], v[186:187], off offset:16
	global_load_dwordx4 v[234:237], v[186:187], off offset:32
	global_load_dwordx4 v[238:241], v[186:187], off offset:48
	global_load_dwordx4 v[242:245], v[186:187], off offset:64
	global_load_dwordx4 v[246:249], v[186:187], off offset:80
	global_load_dwordx4 v[226:229], v[186:187], off offset:96
	s_nop 0
	global_load_dwordx4 v[186:189], v[186:187], off offset:112
	s_mov_b32 s8, 0x3a800000
	s_waitcnt vmcnt(0)
	v_pk_add_f32 v[198:199], v[198:199], v[200:201]
	v_pk_add_f32 v[200:201], v[202:203], v[204:205]
	v_pk_add_f32 v[198:199], v[198:199], 0 op_sel_hi:[1,0]
	v_pk_add_f32 v[202:203], v[234:235], v[236:237]
	v_pk_add_f32 v[198:199], v[198:199], v[200:201]
	v_pk_add_f32 v[204:205], v[238:239], v[240:241]
	v_pk_add_f32 v[198:199], v[198:199], v[202:203]
	v_pk_add_f32 v[206:207], v[242:243], v[244:245]
	v_pk_add_f32 v[198:199], v[198:199], v[204:205]
	v_pk_add_f32 v[214:215], v[246:247], v[248:249]
	v_pk_add_f32 v[198:199], v[198:199], v[206:207]
	v_pk_add_f32 v[226:227], v[226:227], v[228:229]
	v_pk_add_f32 v[198:199], v[198:199], v[214:215]
	v_pk_add_f32 v[186:187], v[186:187], v[188:189]
	v_pk_add_f32 v[198:199], v[198:199], v[226:227]
	v_lshl_add_u32 v188, v196, 3, v225
	v_pk_add_f32 v[186:187], v[198:199], v[186:187]
	s_nop 0
	v_pk_mul_f32 v[186:187], v[186:187], s[8:9] op_sel_hi:[1,0]
	s_nop 0
	v_fma_f32 v187, -v186, v186, v187
	v_max_f32_e32 v187, 0, v187
	v_add_f32_e32 v187, 0x3727c5ac, v187
	v_rsq_f32_e32 v187, v187
	ds_write_b64 v188, v[186:187]

; #define PG8_STAGE(bufoff, gbase, voff) do { _Pragma("unroll") for (int _i = 0; _i < 2; ++_i) \
;         __builtin_amdgcn_global_load_lds((const unsigned*)((const char*)(gbase) + (voff)[_i]), (PG8_LAS unsigned*)(lds + (bufoff) + ldsw + _i * 8192), 16, 0, 0); } while (0)
; #define PG8_LDA(dst, b, h) do { _Pragma("unroll") for (int m = 0; m < 4; ++m) _Pragma("unroll") for (int k = 0; k < 2; ++k) dst[m][k] = *(const PG8_LAS bf16x8*)(lds + PG8_SA(b, h) + aoff + m * 2048 + k * 1024); } while (0)
; #define PG8_LDB(dst, b, h) do { _Pragma("unroll") for (int n = 0; n < 2; ++n) _Pragma("unroll") for (int k = 0; k < 2; ++k) dst[n][k] = *(const PG8_LAS bf16x8*)(lds + PG8_SB(b, h) + boff + n * 2048 + k * 1024); } while (0)
; #define PG8_MMA(ai, bj, At, Bt) do { __builtin_amdgcn_s_setprio(1); _Pragma("unroll") for (int m = 0; m < 4; ++m) _Pragma("unroll") for (int n = 0; n < 2; ++n) _Pragma("unroll") for (int k = 0; k < 2; ++k) \
;         acc[ai][bj][m][n] = __builtin_amdgcn_mfma_f32_16x16x32_bf16(Bt[n][k], At[m][k], acc[ai][bj][m][n], 0, 0, 0); __builtin_amdgcn_s_setprio(0); } while (0)
; #define PG8_WAIT_V(n) asm volatile("s_waitcnt vmcnt(" #n ")" ::: "memory")
; #define PG8_WAIT_L(n) asm volatile("s_waitcnt lgkmcnt(" #n ")" ::: "memory")
; #define PG8_BAR __builtin_amdgcn_s_barrier()
; #define PG8_SCHED __builtin_amdgcn_sched_barrier(0)
; template <class Epi, class Sched, bool ALIGN_EPI = false, bool SP2 = false>
; __device__ __forceinline__ void gemm_phase(PG8_LAS unsigned char* lds, const Gemm g, const Sched& S, const Epi& E, int tid_in) {
;     ...
;             PG8_LDB(B0, 0, 0); PG8_LDB(B1, 0, 1); PG8_SCHED; PG8_LDA(At, 0, 0); PG8_STAGE(PG8_SA(1, 1), a1 + hstep, voffA);
;             PG8_WAIT_V(8); PG8_WAIT_L(0); PG8_BAR; PG8_MMA(0, 0, At, B0); PG8_MMA(0, 1, At, B1); PG8_BAR; PG8_SCHED;
;             PG8_LDA(At, 0, 1); PG8_STAGE(PG8_SB(0, 0), b2, voffB); PG8_STAGE(PG8_SB(0, 1), b2 + hstep, voffB); PG8_STAGE(PG8_SA(0, 0), a2, voffA);
.LBB0_1689:
	s_add_u32 s4, s2, 0x100
	s_addc_u32 s5, s3, 0
	s_add_i32 s65, 0, 0x10000
	s_cmp_eq_u32 s43, 40
	s_cselect_b32 s41, s61, s5
	s_cselect_b32 s40, s60, s4
	s_cselect_b32 s9, s63, s1
	s_cselect_b32 s8, s62, s0
	s_add_i32 s77, 0, 0x14000
	v_add_u32_e32 v126, s65, v202
	v_add_u32_e32 v158, s77, v202
	ds_read_b128 v[90:93], v126
	ds_read_b128 v[102:105], v126 offset:1024
	ds_read_b128 v[114:117], v126 offset:2048
	ds_read_b128 v[126:129], v126 offset:3072
	ds_read_b128 v[138:141], v158
	ds_read_b128 v[150:153], v158 offset:1024
	ds_read_b128 v[154:157], v158 offset:2048
	ds_read_b128 v[158:161], v158 offset:3072
	v_lshl_add_u64 v[208:209], s[2:3], 0, v[168:169]
	s_add_i32 m0, s15, 0xc000
	ds_read_b128 v[172:175], v203
	ds_read_b128 v[176:179], v203 offset:1024
	ds_read_b128 v[180:183], v203 offset:2048
	ds_read_b128 v[184:187], v203 offset:3072
	ds_read_b128 v[188:191], v203 offset:4096
	ds_read_b128 v[192:195], v203 offset:5120
	ds_read_b128 v[196:199], v203 offset:6144
	ds_read_b128 v[204:207], v203 offset:7168
	global_load_lds_dwordx4 v[208:209], off
	v_lshl_add_u64 v[208:209], s[2:3], 0, v[170:171]
	s_add_i32 m0, s15, 0xe000
	s_nop 0
	global_load_lds_dwordx4 v[208:209], off
	s_waitcnt vmcnt(8)
	s_waitcnt lgkmcnt(0)
	s_barrier
	s_setprio 1
	s_waitcnt lgkmcnt(0)
	v_mfma_f32_16x16x32_bf16 v[146:149], v[90:93], v[172:175], v[146:149]
	v_mfma_f32_16x16x32_bf16 v[142:145], v[114:117], v[172:175], v[142:145]
	v_mfma_f32_16x16x32_bf16 v[122:125], v[90:93], v[180:183], v[122:125]
	v_mfma_f32_16x16x32_bf16 v[118:121], v[114:117], v[180:183], v[118:121]
	v_mfma_f32_16x16x32_bf16 v[98:101], v[90:93], v[188:191], v[98:101]
	v_mfma_f32_16x16x32_bf16 v[94:97], v[114:117], v[188:191], v[94:97]
	v_mfma_f32_16x16x32_bf16 v[76:79], v[90:93], v[196:199], v[76:79]
	v_mfma_f32_16x16x32_bf16 v[72:75], v[114:117], v[196:199], v[72:75]
	v_mfma_f32_16x16x32_bf16 v[146:149], v[102:105], v[176:179], v[146:149]
	v_mfma_f32_16x16x32_bf16 v[142:145], v[126:129], v[176:179], v[142:145]
	v_mfma_f32_16x16x32_bf16 v[122:125], v[102:105], v[184:187], v[122:125]
	v_mfma_f32_16x16x32_bf16 v[118:121], v[126:129], v[184:187], v[118:121]
	v_mfma_f32_16x16x32_bf16 v[98:101], v[102:105], v[192:195], v[98:101]
	v_mfma_f32_16x16x32_bf16 v[94:97], v[126:129], v[192:195], v[94:97]
	v_mfma_f32_16x16x32_bf16 v[76:79], v[102:105], v[204:207], v[76:79]
	v_mfma_f32_16x16x32_bf16 v[72:75], v[126:129], v[204:207], v[72:75]
	v_mfma_f32_16x16x32_bf16 v[134:137], v[138:141], v[172:175], v[134:137]
	v_mfma_f32_16x16x32_bf16 v[130:133], v[154:157], v[172:175], v[130:133]
	v_mfma_f32_16x16x32_bf16 v[110:113], v[138:141], v[180:183], v[110:113]
	v_mfma_f32_16x16x32_bf16 v[106:109], v[154:157], v[180:183], v[106:109]
	v_mfma_f32_16x16x32_bf16 v[86:89], v[138:141], v[188:191], v[86:89]
	v_mfma_f32_16x16x32_bf16 v[82:85], v[154:157], v[188:191], v[82:85]
	v_mfma_f32_16x16x32_bf16 v[68:71], v[138:141], v[196:199], v[68:71]
	v_mfma_f32_16x16x32_bf16 v[64:67], v[154:157], v[196:199], v[64:67]
	v_mfma_f32_16x16x32_bf16 v[134:137], v[150:153], v[176:179], v[134:137]
	v_mfma_f32_16x16x32_bf16 v[130:133], v[158:161], v[176:179], v[130:133]
	v_mfma_f32_16x16x32_bf16 v[110:113], v[150:153], v[184:187], v[110:113]
	v_mfma_f32_16x16x32_bf16 v[106:109], v[158:161], v[184:187], v[106:109]
	v_mfma_f32_16x16x32_bf16 v[86:89], v[150:153], v[192:195], v[86:89]
	v_mfma_f32_16x16x32_bf16 v[82:85], v[158:161], v[192:195], v[82:85]
	v_mfma_f32_16x16x32_bf16 v[68:71], v[150:153], v[204:207], v[68:71]
	v_mfma_f32_16x16x32_bf16 v[64:67], v[158:161], v[204:207], v[64:67]
	s_setprio 0
	s_barrier
	s_add_i32 s2, s65, s14
	v_lshl_add_u64 v[208:209], s[8:9], 0, v[80:81]
	s_mov_b32 m0, s2
	ds_read_b128 v[172:175], v203 offset:16384
	ds_read_b128 v[176:179], v203 offset:17408
	ds_read_b128 v[180:183], v203 offset:18432
	ds_read_b128 v[184:187], v203 offset:19456
	ds_read_b128 v[188:191], v203 offset:20480
	ds_read_b128 v[192:195], v203 offset:21504
	ds_read_b128 v[196:199], v203 offset:22528
	ds_read_b128 v[204:207], v203 offset:23552
	global_load_lds_dwordx4 v[208:209], off
	s_add_i32 m0, s2, 0x2000
	s_add_u32 s2, s8, 0xb0000
	v_lshl_add_u64 v[210:211], s[8:9], 0, v[166:167]
	s_addc_u32 s3, s9, 0
	s_add_i32 s65, s77, s14
	global_load_lds_dwordx4 v[210:211], off
	v_lshl_add_u64 v[212:213], s[2:3], 0, v[80:81]
	s_mov_b32 m0, s65
	v_lshl_add_u64 v[214:215], s[40:41], 0, v[164:165]
	global_load_lds_dwordx4 v[212:213], off
	v_lshl_add_u64 v[212:213], s[2:3], 0, v[166:167]
	s_add_i32 m0, s65, 0x2000
	s_nop 0
	global_load_lds_dwordx4 v[212:213], off
	v_lshl_add_u64 v[212:213], s[40:41], 0, v[162:163]
	s_mov_b32 m0, s15
	s_nop 0
	global_load_lds_dwordx4 v[212:213], off
	s_mov_b32 m0, s16
	s_nop 0
	global_load_lds_dwordx4 v[214:215], off
	s_waitcnt vmcnt(8)
	s_waitcnt lgkmcnt(0)
	s_barrier
; #define PG8_STAGE(bufoff, gbase, voff) do { _Pragma("unroll") for (int _i = 0; _i < 2; ++_i) \
;         __builtin_amdgcn_global_load_lds((const unsigned*)((const char*)(gbase) + (voff)[_i]), (PG8_LAS unsigned*)(lds + (bufoff) + ldsw + _i * 8192), 16, 0, 0); } while (0)
; #define PG8_LDA(dst, b, h) do { _Pragma("unroll") for (int m = 0; m < 4; ++m) _Pragma("unroll") for (int k = 0; k < 2; ++k) dst[m][k] = *(const PG8_LAS bf16x8*)(lds + PG8_SA(b, h) + aoff + m * 2048 + k * 1024); } while (0)
; #define PG8_LDB(dst, b, h) do { _Pragma("unroll") for (int n = 0; n < 2; ++n) _Pragma("unroll") for (int k = 0; k < 2; ++k) dst[n][k] = *(const PG8_LAS bf16x8*)(lds + PG8_SB(b, h) + boff + n * 2048 + k * 1024); } while (0)
; #define PG8_MMA(ai, bj, At, Bt) do { __builtin_amdgcn_s_setprio(1); _Pragma("unroll") for (int m = 0; m < 4; ++m) _Pragma("unroll") for (int n = 0; n < 2; ++n) _Pragma("unroll") for (int k = 0; k < 2; ++k) \
;         acc[ai][bj][m][n] = __builtin_amdgcn_mfma_f32_16x16x32_bf16(Bt[n][k], At[m][k], acc[ai][bj][m][n], 0, 0, 0); __builtin_amdgcn_s_setprio(0); } while (0)
; #define PG8_WAIT_V(n) asm volatile("s_waitcnt vmcnt(" #n ")" ::: "memory")
; #define PG8_WAIT_L(n) asm volatile("s_waitcnt lgkmcnt(" #n ")" ::: "memory")
; #define PG8_BAR __builtin_amdgcn_s_barrier()
; #define PG8_SCHED __builtin_amdgcn_sched_barrier(0)
; template <class Epi, class Sched, bool ALIGN_EPI = false, bool SP2 = false>
; __device__ __forceinline__ void gemm_phase(PG8_LAS unsigned char* lds, const Gemm g, const Sched& S, const Epi& E, int tid_in) {
;     ...
;             PG8_WAIT_V(8); PG8_WAIT_L(0); PG8_BAR; PG8_MMA(1, 0, At, B0); PG8_MMA(1, 1, At, B1); PG8_BAR; PG8_SCHED;
;             PG8_LDB(B0, 1, 0); PG8_LDB(B1, 1, 1); PG8_SCHED; PG8_LDA(At, 1, 0); PG8_STAGE(PG8_SA(0, 1), a2 + hstep, voffA);
;             PG8_WAIT_V(8); PG8_WAIT_L(0); PG8_BAR; PG8_MMA(0, 0, At, B0); PG8_MMA(0, 1, At, B1); PG8_BAR; PG8_SCHED;
	s_setprio 1
	s_waitcnt lgkmcnt(0)
	v_mfma_f32_16x16x32_bf16 v[60:63], v[90:93], v[172:175], v[60:63]
	v_mfma_f32_16x16x32_bf16 v[56:59], v[114:117], v[172:175], v[56:59]
	v_mfma_f32_16x16x32_bf16 v[44:47], v[90:93], v[180:183], v[44:47]
	v_mfma_f32_16x16x32_bf16 v[40:43], v[114:117], v[180:183], v[40:43]
	v_mfma_f32_16x16x32_bf16 v[28:31], v[90:93], v[188:191], v[28:31]
	v_mfma_f32_16x16x32_bf16 v[24:27], v[114:117], v[188:191], v[24:27]
	v_mfma_f32_16x16x32_bf16 v[12:15], v[90:93], v[196:199], v[12:15]
	v_mfma_f32_16x16x32_bf16 v[8:11], v[114:117], v[196:199], v[8:11]
	v_mfma_f32_16x16x32_bf16 v[60:63], v[102:105], v[176:179], v[60:63]
	v_mfma_f32_16x16x32_bf16 v[56:59], v[126:129], v[176:179], v[56:59]
	v_mfma_f32_16x16x32_bf16 v[44:47], v[102:105], v[184:187], v[44:47]
	v_mfma_f32_16x16x32_bf16 v[40:43], v[126:129], v[184:187], v[40:43]
	v_mfma_f32_16x16x32_bf16 v[28:31], v[102:105], v[192:195], v[28:31]
	v_mfma_f32_16x16x32_bf16 v[24:27], v[126:129], v[192:195], v[24:27]
	v_mfma_f32_16x16x32_bf16 v[12:15], v[102:105], v[204:207], v[12:15]
	v_mfma_f32_16x16x32_bf16 v[8:11], v[126:129], v[204:207], v[8:11]
	v_mfma_f32_16x16x32_bf16 v[52:55], v[138:141], v[172:175], v[52:55]
	v_mfma_f32_16x16x32_bf16 v[48:51], v[154:157], v[172:175], v[48:51]
	v_mfma_f32_16x16x32_bf16 v[36:39], v[138:141], v[180:183], v[36:39]
	v_mfma_f32_16x16x32_bf16 v[32:35], v[154:157], v[180:183], v[32:35]
	v_mfma_f32_16x16x32_bf16 v[20:23], v[138:141], v[188:191], v[20:23]
	v_mfma_f32_16x16x32_bf16 v[16:19], v[154:157], v[188:191], v[16:19]
	v_mfma_f32_16x16x32_bf16 v[4:7], v[138:141], v[196:199], v[4:7]
	v_mfma_f32_16x16x32_bf16 v[0:3], v[154:157], v[196:199], v[0:3]
	v_mfma_f32_16x16x32_bf16 v[52:55], v[150:153], v[176:179], v[52:55]
	v_mfma_f32_16x16x32_bf16 v[48:51], v[158:161], v[176:179], v[48:51]
	v_mfma_f32_16x16x32_bf16 v[36:39], v[150:153], v[184:187], v[36:39]
	v_mfma_f32_16x16x32_bf16 v[32:35], v[158:161], v[184:187], v[32:35]
	v_mfma_f32_16x16x32_bf16 v[20:23], v[150:153], v[192:195], v[20:23]
	v_mfma_f32_16x16x32_bf16 v[16:19], v[158:161], v[192:195], v[16:19]
	v_mfma_f32_16x16x32_bf16 v[4:7], v[150:153], v[204:207], v[4:7]
	v_mfma_f32_16x16x32_bf16 v[0:3], v[158:161], v[204:207], v[0:3]
	s_setprio 0
	s_barrier
	s_add_i32 s65, 0, 0x18000
	s_add_i32 s77, 0, 0x1c000
	v_add_u32_e32 v126, s65, v202
	v_add_u32_e32 v158, s77, v202
	ds_read_b128 v[90:93], v126
	ds_read_b128 v[102:105], v126 offset:1024
	ds_read_b128 v[114:117], v126 offset:2048
	ds_read_b128 v[126:129], v126 offset:3072
	ds_read_b128 v[138:141], v158
	ds_read_b128 v[150:153], v158 offset:1024
	ds_read_b128 v[154:157], v158 offset:2048
	ds_read_b128 v[158:161], v158 offset:3072
	s_add_u32 s2, s40, 0xb0000
	s_addc_u32 s3, s41, 0
	s_mov_b32 m0, s17
	v_lshl_add_u64 v[226:227], s[2:3], 0, v[162:163]
	ds_read_b128 v[172:175], v203 offset:32768
	ds_read_b128 v[176:179], v203 offset:33792
	ds_read_b128 v[180:183], v203 offset:34816
	ds_read_b128 v[184:187], v203 offset:35840
	ds_read_b128 v[188:191], v203 offset:36864
	ds_read_b128 v[192:195], v203 offset:37888
	ds_read_b128 v[196:199], v203 offset:38912
	ds_read_b128 v[204:207], v203 offset:39936
	global_load_lds_dwordx4 v[226:227], off
	v_lshl_add_u64 v[226:227], s[2:3], 0, v[164:165]
	s_mov_b32 m0, s18
	s_nop 0
	global_load_lds_dwordx4 v[226:227], off
	s_waitcnt vmcnt(8)
	s_waitcnt lgkmcnt(0)
	s_barrier
	s_setprio 1
	s_waitcnt lgkmcnt(0)
	v_mfma_f32_16x16x32_bf16 v[146:149], v[90:93], v[172:175], v[146:149]
	v_mfma_f32_16x16x32_bf16 v[142:145], v[114:117], v[172:175], v[142:145]
	v_mfma_f32_16x16x32_bf16 v[122:125], v[90:93], v[180:183], v[122:125]
	v_mfma_f32_16x16x32_bf16 v[118:121], v[114:117], v[180:183], v[118:121]
	v_mfma_f32_16x16x32_bf16 v[98:101], v[90:93], v[188:191], v[98:101]
	v_mfma_f32_16x16x32_bf16 v[94:97], v[114:117], v[188:191], v[94:97]
	v_mfma_f32_16x16x32_bf16 v[76:79], v[90:93], v[196:199], v[76:79]
	v_mfma_f32_16x16x32_bf16 v[72:75], v[114:117], v[196:199], v[72:75]
	v_mfma_f32_16x16x32_bf16 v[146:149], v[102:105], v[176:179], v[146:149]
	v_mfma_f32_16x16x32_bf16 v[142:145], v[126:129], v[176:179], v[142:145]
	v_mfma_f32_16x16x32_bf16 v[122:125], v[102:105], v[184:187], v[122:125]
	v_mfma_f32_16x16x32_bf16 v[118:121], v[126:129], v[184:187], v[118:121]
	v_mfma_f32_16x16x32_bf16 v[98:101], v[102:105], v[192:195], v[98:101]
	v_mfma_f32_16x16x32_bf16 v[94:97], v[126:129], v[192:195], v[94:97]
	v_mfma_f32_16x16x32_bf16 v[76:79], v[102:105], v[204:207], v[76:79]
	v_mfma_f32_16x16x32_bf16 v[72:75], v[126:129], v[204:207], v[72:75]
	v_mfma_f32_16x16x32_bf16 v[134:137], v[138:141], v[172:175], v[134:137]
	v_mfma_f32_16x16x32_bf16 v[130:133], v[154:157], v[172:175], v[130:133]
	v_mfma_f32_16x16x32_bf16 v[110:113], v[138:141], v[180:183], v[110:113]
	v_mfma_f32_16x16x32_bf16 v[106:109], v[154:157], v[180:183], v[106:109]
	v_mfma_f32_16x16x32_bf16 v[86:89], v[138:141], v[188:191], v[86:89]
	v_mfma_f32_16x16x32_bf16 v[82:85], v[154:157], v[188:191], v[82:85]
	v_mfma_f32_16x16x32_bf16 v[68:71], v[138:141], v[196:199], v[68:71]
	v_mfma_f32_16x16x32_bf16 v[64:67], v[154:157], v[196:199], v[64:67]
	v_mfma_f32_16x16x32_bf16 v[134:137], v[150:153], v[176:179], v[134:137]
	v_mfma_f32_16x16x32_bf16 v[130:133], v[158:161], v[176:179], v[130:133]
	v_mfma_f32_16x16x32_bf16 v[110:113], v[150:153], v[184:187], v[110:113]
	v_mfma_f32_16x16x32_bf16 v[106:109], v[158:161], v[184:187], v[106:109]
	v_mfma_f32_16x16x32_bf16 v[86:89], v[150:153], v[192:195], v[86:89]
	v_mfma_f32_16x16x32_bf16 v[82:85], v[158:161], v[192:195], v[82:85]
	v_mfma_f32_16x16x32_bf16 v[68:71], v[150:153], v[204:207], v[68:71]
	v_mfma_f32_16x16x32_bf16 v[64:67], v[158:161], v[204:207], v[64:67]
	s_setprio 0
	s_barrier
; #define PG8_STAGE(bufoff, gbase, voff) do { _Pragma("unroll") for (int _i = 0; _i < 2; ++_i) \
;         __builtin_amdgcn_global_load_lds((const unsigned*)((const char*)(gbase) + (voff)[_i]), (PG8_LAS unsigned*)(lds + (bufoff) + ldsw + _i * 8192), 16, 0, 0); } while (0)
; #define PG8_LDA(dst, b, h) do { _Pragma("unroll") for (int m = 0; m < 4; ++m) _Pragma("unroll") for (int k = 0; k < 2; ++k) dst[m][k] = *(const PG8_LAS bf16x8*)(lds + PG8_SA(b, h) + aoff + m * 2048 + k * 1024); } while (0)
; #define PG8_MMA(ai, bj, At, Bt) do { __builtin_amdgcn_s_setprio(1); _Pragma("unroll") for (int m = 0; m < 4; ++m) _Pragma("unroll") for (int n = 0; n < 2; ++n) _Pragma("unroll") for (int k = 0; k < 2; ++k) \
;         acc[ai][bj][m][n] = __builtin_amdgcn_mfma_f32_16x16x32_bf16(Bt[n][k], At[m][k], acc[ai][bj][m][n], 0, 0, 0); __builtin_amdgcn_s_setprio(0); } while (0)
; #define PG8_WAIT_V(n) asm volatile("s_waitcnt vmcnt(" #n ")" ::: "memory")
; #define PG8_WAIT_L(n) asm volatile("s_waitcnt lgkmcnt(" #n ")" ::: "memory")
; #define PG8_BAR __builtin_amdgcn_s_barrier()
; #define PG8_SCHED __builtin_amdgcn_sched_barrier(0)
; template <class Epi, class Sched, bool ALIGN_EPI = false, bool SP2 = false>
; __device__ __forceinline__ void gemm_phase(PG8_LAS unsigned char* lds, const Gemm g, const Sched& S, const Epi& E, int tid_in) {
;     ...
;             PG8_LDA(At, 1, 1); PG8_STAGE(PG8_SB(1, 0), b3, voffB); PG8_STAGE(PG8_SB(1, 1), b3 + hstep, voffB); PG8_STAGE(PG8_SA(1, 0), a3, voffA);
;             PG8_WAIT_V(8); PG8_WAIT_L(0); PG8_BAR; PG8_MMA(1, 0, At, B0); PG8_MMA(1, 1, At, B1); PG8_BAR; PG8_SCHED;
;     __device__ __forceinline__ void operator()(const pg8::f32x4 (&acc)[2][2][4][2], const pg8::Unit& u, int wr, int wc, int fr, int fq) const {
;     ...
;         const int col0 = u.pn * 256 + wc * 32 + 8 * fq;
; #pragma unroll
;         for (int ai = 0; ai < 2; ++ai) {
;             u32x4 zx[4][2];
; #pragma unroll
;             for (int m = 0; m < 4; ++m)
; #pragma unroll
;                 for (int bj = 0; bj < 2; ++bj) zx[m][bj] = *(const u32x4*)(ZB + (size_t)(u.pm * 256 + ai * 128 + wr * 64 + m * 16 + fr) * 1024 + col0 + bj * 128);
	s_add_i32 s2, s65, s14
	v_lshl_add_u64 v[208:209], v[208:209], 0, s[6:7]
	s_mov_b32 m0, s2
	ds_read_b128 v[172:175], v203 offset:49152
	ds_read_b128 v[176:179], v203 offset:50176
	ds_read_b128 v[180:183], v203 offset:51200
	ds_read_b128 v[184:187], v203 offset:52224
	ds_read_b128 v[188:191], v203 offset:53248
	ds_read_b128 v[192:195], v203 offset:54272
	ds_read_b128 v[196:199], v203 offset:55296
	ds_read_b128 v[204:207], v203 offset:56320
	global_load_lds_dwordx4 v[208:209], off
	s_add_i32 m0, s2, 0x2000
	s_add_u32 s2, s8, 0xb0080
	v_lshl_add_u64 v[208:209], v[210:211], 0, s[6:7]
	s_addc_u32 s3, s9, 0
	s_add_i32 s8, s77, s14
	global_load_lds_dwordx4 v[208:209], off
	v_lshl_add_u64 v[208:209], s[2:3], 0, v[80:81]
	s_mov_b32 m0, s8
	s_nop 0
	global_load_lds_dwordx4 v[208:209], off
	v_lshl_add_u64 v[208:209], s[2:3], 0, v[166:167]
	s_add_i32 m0, s8, 0x2000
	s_nop 0
	global_load_lds_dwordx4 v[208:209], off
	v_lshl_add_u64 v[208:209], v[212:213], 0, s[6:7]
	s_mov_b32 m0, s67
	s_nop 0
	global_load_lds_dwordx4 v[208:209], off
	v_lshl_add_u64 v[208:209], v[214:215], 0, s[6:7]
	s_mov_b32 m0, s68
	s_nop 0
	global_load_lds_dwordx4 v[208:209], off
	s_waitcnt vmcnt(8)
	s_waitcnt lgkmcnt(0)
	s_barrier
	s_setprio 1
	s_waitcnt lgkmcnt(0)
	v_mfma_f32_16x16x32_bf16 v[60:63], v[90:93], v[172:175], v[60:63]
	v_mfma_f32_16x16x32_bf16 v[56:59], v[114:117], v[172:175], v[56:59]
	v_mfma_f32_16x16x32_bf16 v[44:47], v[90:93], v[180:183], v[44:47]
	v_mfma_f32_16x16x32_bf16 v[40:43], v[114:117], v[180:183], v[40:43]
	v_mfma_f32_16x16x32_bf16 v[28:31], v[90:93], v[188:191], v[28:31]
	v_mfma_f32_16x16x32_bf16 v[24:27], v[114:117], v[188:191], v[24:27]
	v_mfma_f32_16x16x32_bf16 v[12:15], v[90:93], v[196:199], v[12:15]
	v_mfma_f32_16x16x32_bf16 v[8:11], v[114:117], v[196:199], v[8:11]
	v_mfma_f32_16x16x32_bf16 v[60:63], v[102:105], v[176:179], v[60:63]
	v_mfma_f32_16x16x32_bf16 v[56:59], v[126:129], v[176:179], v[56:59]
	v_mfma_f32_16x16x32_bf16 v[44:47], v[102:105], v[184:187], v[44:47]
	v_mfma_f32_16x16x32_bf16 v[40:43], v[126:129], v[184:187], v[40:43]
	v_mfma_f32_16x16x32_bf16 v[28:31], v[102:105], v[192:195], v[28:31]
	v_mfma_f32_16x16x32_bf16 v[24:27], v[126:129], v[192:195], v[24:27]
	v_mfma_f32_16x16x32_bf16 v[12:15], v[102:105], v[204:207], v[12:15]
	v_mfma_f32_16x16x32_bf16 v[8:11], v[126:129], v[204:207], v[8:11]
	v_mfma_f32_16x16x32_bf16 v[52:55], v[138:141], v[172:175], v[52:55]
	v_mfma_f32_16x16x32_bf16 v[48:51], v[154:157], v[172:175], v[48:51]
	v_mfma_f32_16x16x32_bf16 v[36:39], v[138:141], v[180:183], v[36:39]
	v_mfma_f32_16x16x32_bf16 v[32:35], v[154:157], v[180:183], v[32:35]
	v_mfma_f32_16x16x32_bf16 v[20:23], v[138:141], v[188:191], v[20:23]
	v_mfma_f32_16x16x32_bf16 v[16:19], v[154:157], v[188:191], v[16:19]
	v_mfma_f32_16x16x32_bf16 v[4:7], v[138:141], v[196:199], v[4:7]
	v_mfma_f32_16x16x32_bf16 v[0:3], v[154:157], v[196:199], v[0:3]
	v_mfma_f32_16x16x32_bf16 v[52:55], v[150:153], v[176:179], v[52:55]
	v_mfma_f32_16x16x32_bf16 v[48:51], v[158:161], v[176:179], v[48:51]
	v_mfma_f32_16x16x32_bf16 v[36:39], v[150:153], v[184:187], v[36:39]
	v_mfma_f32_16x16x32_bf16 v[32:35], v[158:161], v[184:187], v[32:35]
	v_mfma_f32_16x16x32_bf16 v[20:23], v[150:153], v[192:195], v[20:23]
	v_mfma_f32_16x16x32_bf16 v[16:19], v[158:161], v[192:195], v[16:19]
	v_mfma_f32_16x16x32_bf16 v[4:7], v[150:153], v[204:207], v[4:7]
	v_mfma_f32_16x16x32_bf16 v[0:3], v[158:161], v[204:207], v[0:3]
	s_setprio 0
	s_barrier
	s_add_i32 s43, s43, 2
	s_add_u32 s0, s0, 0x100
	s_addc_u32 s1, s1, 0
	s_cmp_gt_u32 s43, 41
	s_mov_b64 s[2:3], s[4:5]
	s_cbranch_scc0 .LBB0_1689
	v_mov_b32_e32 v197, v201
	v_mov_b32_e32 v205, v200
	s_lshl_b32 s0, s64, 8
	s_or_b32 s0, s0, s66
	s_lshl_b32 s3, s42, 8
	v_add_u32_e32 v196, s19, v197
	v_lshl_add_u32 v172, v205, 3, s0
	v_and_b32_e32 v186, 0xffffff00, v172
	v_and_b32_e32 v187, 0xff, v216
	v_add_lshl_u32 v186, v186, v187, 2
	v_mov_b32_e32 v187, 0
	v_cmp_gt_u32_e32 vcc, 0x100, v216
	v_mov_b32_e32 v188, s50
	v_mov_b32_e32 v189, s51
	s_and_saveexec_b64 vcc, vcc
	v_mov_b32_e32 v188, s48
	v_mov_b32_e32 v189, s49
	s_mov_b64 exec, vcc
	v_lshl_add_u64 v[188:189], v[188:189], 0, v[186:187]
	global_load_dword v186, v[188:189], off
	v_lshlrev_b32_e32 v187, 2, v216
	v_add_u32_e32 v187, 0x21000, v187
	v_and_b32_e32 v80, 0xff, v172
	v_lshlrev_b32_e32 v80, 2, v80
	v_add_u32_e32 v80, 0x21000, v80
	v_add_u32_e32 v176, s3, v196
	v_ashrrev_i32_e32 v173, 31, v172
	v_ashrrev_i32_e32 v177, 31, v176
	v_add_u32_e32 v190, 16, v176
	v_lshl_add_u64 v[174:175], v[172:173], 1, s[20:21]
	v_lshlrev_b64 v[194:195], 11, v[176:177]
	v_ashrrev_i32_e32 v191, 31, v190
	v_add_u32_e32 v182, 32, v176
	v_lshl_add_u64 v[90:91], v[174:175], 0, v[194:195]
	v_lshlrev_b64 v[192:193], 11, v[190:191]
	v_ashrrev_i32_e32 v183, 31, v182
	v_add_u32_e32 v178, 48, v176
	global_load_dwordx4 v[158:161], v[90:91], off
	global_load_dwordx4 v[154:157], v[90:91], off offset:256
	v_lshl_add_u64 v[90:91], v[174:175], 0, v[192:193]
	v_lshlrev_b64 v[184:185], 11, v[182:183]
	v_ashrrev_i32_e32 v179, 31, v178
	global_load_dwordx4 v[150:153], v[90:91], off
	global_load_dwordx4 v[138:141], v[90:91], off offset:256
	v_lshl_add_u64 v[90:91], v[174:175], 0, v[184:185]
	v_lshlrev_b64 v[180:181], 11, v[178:179]
	global_load_dwordx4 v[126:129], v[90:91], off
	global_load_dwordx4 v[114:117], v[90:91], off offset:256
	v_lshl_add_u64 v[90:91], v[174:175], 0, v[180:181]
	global_load_dwordx4 v[102:105], v[90:91], off
	s_nop 0
	global_load_dwordx4 v[90:93], v[90:91], off offset:256
	s_and_b64 vcc, exec, s[58:59]
	s_cbranch_vccz .LBB0_1692
	s_barrier
; __device__ __forceinline__ void ln_table(const float* st, int pm, int key, int wr, int wc, int fr, int fq) {
;     ...
;     if (st) {
;         const int want = key * 128 + pm + 1;
;         if (__builtin_amdgcn_readfirstlane(*kw) != want) {
;             if (t < 256) {
;                 const f32x4* p = (const f32x4*)(st + ((size_t)(pm * 256 + t)) * 32);
;                 float s = 0.f, q = 0.f;
; #pragma unroll
;                 for (int i = 0; i < 8; ++i) { const f32x4 v = p[i]; s += v[0] + v[2]; q += v[1] + v[3]; }
;                 const float mu = s * (1.f / D);
;                 tab[t] = (f32x2v){mu, __builtin_amdgcn_rsqf(fmaxf(q * (1.f / D) - mu * mu, 0.f) + LN_EPS)};
.LBB0_1692:
	s_waitcnt vmcnt(8)
	ds_write_b32 v187, v186
	ds_read_b32 v186, v223
	s_add_i32 s2, s73, s42
	s_waitcnt lgkmcnt(0)
	v_readfirstlane_b32 s0, v186
	s_cmp_eq_u32 s0, s2
	s_cbranch_scc1 .LBB0_1698
	v_lshlrev_b32_e32 v186, 4, v205
	v_add3_u32 v197, s69, v197, v186
	s_movk_i32 s0, 0x100
	v_cmp_gt_i32_e32 vcc, s0, v197
	s_and_saveexec_b64 s[0:1], vcc
	s_cbranch_execz .LBB0_1695
	v_add_u32_e32 v186, s3, v197
	v_ashrrev_i32_e32 v187, 31, v186
	v_lshlrev_b64 v[186:187], 7, v[186:187]
	v_lshl_add_u64 v[198:199], s[44:45], 0, v[186:187]
	global_load_dwordx4 v[186:189], v[198:199], off
	global_load_dwordx4 v[206:209], v[198:199], off offset:16
	global_load_dwordx4 v[210:213], v[198:199], off offset:32
	global_load_dwordx4 v[226:229], v[198:199], off offset:48
	global_load_dwordx4 v[234:237], v[198:199], off offset:64
	global_load_dwordx4 v[238:241], v[198:199], off offset:80
	global_load_dwordx4 v[242:245], v[198:199], off offset:96
	global_load_dwordx4 v[246:249], v[198:199], off offset:112
	s_mov_b32 s4, 0x3a800000
	s_waitcnt vmcnt(0)
	v_pk_add_f32 v[186:187], v[186:187], v[188:189]
	v_pk_add_f32 v[188:189], v[206:207], v[208:209]
	v_pk_add_f32 v[186:187], v[186:187], 0 op_sel_hi:[1,0]
	v_pk_add_f32 v[198:199], v[210:211], v[212:213]
	v_pk_add_f32 v[186:187], v[186:187], v[188:189]
	v_pk_add_f32 v[206:207], v[226:227], v[228:229]
	v_pk_add_f32 v[186:187], v[186:187], v[198:199]
	v_pk_add_f32 v[208:209], v[234:235], v[236:237]
	v_pk_add_f32 v[186:187], v[186:187], v[206:207]
	v_pk_add_f32 v[210:211], v[238:239], v[240:241]
	v_pk_add_f32 v[186:187], v[186:187], v[208:209]
	v_pk_add_f32 v[212:213], v[242:243], v[244:245]
	v_pk_add_f32 v[186:187], v[186:187], v[210:211]
	v_pk_add_f32 v[188:189], v[246:247], v[248:249]
	v_pk_add_f32 v[186:187], v[186:187], v[212:213]
	s_nop 0
	v_pk_add_f32 v[186:187], v[186:187], v[188:189]
	v_lshl_add_u32 v188, v197, 3, v225
	v_pk_mul_f32 v[186:187], v[186:187], s[4:5] op_sel_hi:[1,0]
	s_nop 0
	v_fma_f32 v187, -v186, v186, v187
	v_max_f32_e32 v187, 0, v187
	v_add_f32_e32 v187, 0x3727c5ac, v187
	v_rsq_f32_e32 v187, v187
	ds_write_b64 v188, v[186:187]
